# v42 minus the 18 redundant s_waitcnt lgkmcnt(0) right after each K-loop barrier (same wait already precedes the barrier, no LDS op in between)
# speedup vs baseline: 1.0052x; 1.0003x over previous
.LBB0_306:
	s_ashr_i32 s51, s50, 31
	s_lshl_b64 s[12:13], s[50:51], 19
	s_add_u32 s52, s8, s12
	s_addc_u32 s53, s9, s13
	s_and_b64 s[12:13], s[38:39], exec
	s_cselect_b32 s73, s53, s57
	s_cselect_b32 s74, s52, s56
	s_ashr_i32 s49, s48, 31
	s_lshl_b64 s[12:13], s[48:49], 19
	s_add_u32 s54, s2, s12
	s_addc_u32 s55, s16, s13
	s_and_b64 s[12:13], s[38:39], exec
	s_cselect_b32 s75, s55, s59
	s_cselect_b32 s76, s54, s58
	s_lshl_b64 s[12:13], s[50:51], 11
	v_lshl_add_u64 v[50:51], v[166:167], 0, s[12:13]
	s_lshl_b32 s12, s71, 12
	s_and_b32 s51, s12, 0x1000
	s_lshl_b64 s[12:13], s[48:49], 10
	s_add_u32 s56, s56, 0x40080
	s_addc_u32 s57, s57, 0
	v_lshl_add_u64 v[52:53], v[168:169], 0, s[12:13]
	s_add_u32 s12, s58, 0x100
	s_addc_u32 s13, s59, 0
	s_add_i32 s51, s23, s51
	s_mov_b32 s49, -2
	s_add_i32 s77, s51, 0x800
	s_mov_b64 s[58:59], 0
	s_add_u32 s60, s56, 0xfffc0080
	s_addc_u32 s61, s57, -1
	s_and_b64 s[58:59], s[58:59], exec
	s_cselect_b32 s61, s73, s61
	s_cselect_b32 s60, s74, s60
	s_cselect_b32 s59, s75, s13
	s_cselect_b32 s58, s76, s12
	s_add_i32 s80, 0, 0x10000
	s_add_i32 s82, 0, 0x14000
	v_add_u32_e32 v146, s80, v165
	v_add_u32_e32 v182, s82, v165
	ds_read_b128 v[54:57], v146
	ds_read_b128 v[66:69], v146 offset:1024
	ds_read_b128 v[70:73], v146 offset:2048
	ds_read_b128 v[146:149], v146 offset:3072
	ds_read_b128 v[150:153], v182
	ds_read_b128 v[174:177], v182 offset:1024
	ds_read_b128 v[178:181], v182 offset:2048
	ds_read_b128 v[182:185], v182 offset:3072
	v_lshl_add_u64 v[224:225], s[56:57], 0, v[170:171]
	s_add_i32 m0, s64, 0xc000
	ds_read_b128 v[190:193], v188
	ds_read_b128 v[194:197], v188 offset:1024
	ds_read_b128 v[198:201], v188 offset:2048
	ds_read_b128 v[202:205], v188 offset:3072
	ds_read_b128 v[208:211], v188 offset:4096
	ds_read_b128 v[212:215], v188 offset:5120
	ds_read_b128 v[216:219], v188 offset:6144
	ds_read_b128 v[220:223], v188 offset:7168
	global_load_lds_dwordx4 v[224:225], off
	v_lshl_add_u64 v[224:225], s[56:57], 0, v[172:173]
	s_add_i32 m0, s64, 0xe000
	s_nop 0
	global_load_lds_dwordx4 v[224:225], off
	s_waitcnt vmcnt(8)
	s_waitcnt lgkmcnt(0)
	s_barrier
	s_setprio 1
	v_mfma_f32_16x16x32_bf16 v[142:145], v[54:57], v[190:193], 0
	v_mfma_f32_16x16x32_bf16 v[134:137], v[70:73], v[190:193], 0
	v_mfma_f32_16x16x32_bf16 v[126:129], v[54:57], v[198:201], 0
	v_mfma_f32_16x16x32_bf16 v[118:121], v[70:73], v[198:201], 0
	v_mfma_f32_16x16x32_bf16 v[110:113], v[54:57], v[208:211], 0
	v_mfma_f32_16x16x32_bf16 v[102:105], v[70:73], v[208:211], 0
	v_mfma_f32_16x16x32_bf16 v[94:97], v[54:57], v[216:219], 0
	v_mfma_f32_16x16x32_bf16 v[86:89], v[70:73], v[216:219], 0
	v_mfma_f32_16x16x32_bf16 v[142:145], v[66:69], v[194:197], v[142:145]
	v_mfma_f32_16x16x32_bf16 v[134:137], v[146:149], v[194:197], v[134:137]
	v_mfma_f32_16x16x32_bf16 v[126:129], v[66:69], v[202:205], v[126:129]
	v_mfma_f32_16x16x32_bf16 v[118:121], v[146:149], v[202:205], v[118:121]
	v_mfma_f32_16x16x32_bf16 v[110:113], v[66:69], v[212:215], v[110:113]
	v_mfma_f32_16x16x32_bf16 v[102:105], v[146:149], v[212:215], v[102:105]
	v_mfma_f32_16x16x32_bf16 v[94:97], v[66:69], v[220:223], v[94:97]
	v_mfma_f32_16x16x32_bf16 v[86:89], v[146:149], v[220:223], v[86:89]
	v_mfma_f32_16x16x32_bf16 v[138:141], v[150:153], v[190:193], 0
	v_mfma_f32_16x16x32_bf16 v[130:133], v[178:181], v[190:193], 0
	v_mfma_f32_16x16x32_bf16 v[122:125], v[150:153], v[198:201], 0
	v_mfma_f32_16x16x32_bf16 v[114:117], v[178:181], v[198:201], 0
	v_mfma_f32_16x16x32_bf16 v[106:109], v[150:153], v[208:211], 0
	v_mfma_f32_16x16x32_bf16 v[98:101], v[178:181], v[208:211], 0
	v_mfma_f32_16x16x32_bf16 v[90:93], v[150:153], v[216:219], 0
	v_mfma_f32_16x16x32_bf16 v[82:85], v[178:181], v[216:219], 0
	v_mfma_f32_16x16x32_bf16 v[138:141], v[174:177], v[194:197], v[138:141]
	v_mfma_f32_16x16x32_bf16 v[130:133], v[182:185], v[194:197], v[130:133]
	v_mfma_f32_16x16x32_bf16 v[122:125], v[174:177], v[202:205], v[122:125]
	v_mfma_f32_16x16x32_bf16 v[114:117], v[182:185], v[202:205], v[114:117]
	v_mfma_f32_16x16x32_bf16 v[106:109], v[174:177], v[212:215], v[106:109]
	v_mfma_f32_16x16x32_bf16 v[98:101], v[182:185], v[212:215], v[98:101]
	v_mfma_f32_16x16x32_bf16 v[90:93], v[174:177], v[220:223], v[90:93]
	v_mfma_f32_16x16x32_bf16 v[82:85], v[182:185], v[220:223], v[82:85]
	s_setprio 0
	s_barrier
	s_add_i32 s80, s80, s22
	v_lshl_add_u64 v[224:225], s[58:59], 0, v[158:159]
	s_mov_b32 m0, s80
	ds_read_b128 v[190:193], v188 offset:16384
	ds_read_b128 v[194:197], v188 offset:17408
	ds_read_b128 v[198:201], v188 offset:18432
	ds_read_b128 v[202:205], v188 offset:19456
	ds_read_b128 v[208:211], v188 offset:20480
	ds_read_b128 v[212:215], v188 offset:21504
	ds_read_b128 v[216:219], v188 offset:22528
	ds_read_b128 v[220:223], v188 offset:23552
	global_load_lds_dwordx4 v[224:225], off
	s_add_i32 m0, s80, 0x2000
	s_add_u32 s80, s58, 0x40000
	v_lshl_add_u64 v[226:227], s[58:59], 0, v[154:155]
	s_addc_u32 s81, s59, 0
	s_add_i32 s82, s82, s22
	global_load_lds_dwordx4 v[226:227], off
	v_lshl_add_u64 v[228:229], s[80:81], 0, v[158:159]
	s_mov_b32 m0, s82
	v_lshl_add_u64 v[230:231], s[60:61], 0, v[156:157]
	global_load_lds_dwordx4 v[228:229], off
	v_lshl_add_u64 v[228:229], s[80:81], 0, v[154:155]
	s_add_i32 m0, s82, 0x2000
	s_nop 0
	global_load_lds_dwordx4 v[228:229], off
	v_lshl_add_u64 v[228:229], s[60:61], 0, v[160:161]
	s_mov_b32 m0, s64
	s_nop 0
	global_load_lds_dwordx4 v[228:229], off
	s_mov_b32 m0, s65
	s_nop 0
	global_load_lds_dwordx4 v[230:231], off
	s_waitcnt vmcnt(8)
	s_waitcnt lgkmcnt(0)
	s_barrier
	s_setprio 1
	v_mfma_f32_16x16x32_bf16 v[78:81], v[54:57], v[190:193], 0
	v_mfma_f32_16x16x32_bf16 v[62:65], v[70:73], v[190:193], 0
	v_mfma_f32_16x16x32_bf16 v[46:49], v[54:57], v[198:201], 0
	v_mfma_f32_16x16x32_bf16 v[38:41], v[70:73], v[198:201], 0
	v_mfma_f32_16x16x32_bf16 v[30:33], v[54:57], v[208:211], 0
	v_mfma_f32_16x16x32_bf16 v[22:25], v[70:73], v[208:211], 0
	v_mfma_f32_16x16x32_bf16 v[14:17], v[54:57], v[216:219], 0
	v_mfma_f32_16x16x32_bf16 v[6:9], v[70:73], v[216:219], 0
	v_mfma_f32_16x16x32_bf16 v[78:81], v[66:69], v[194:197], v[78:81]
	v_mfma_f32_16x16x32_bf16 v[62:65], v[146:149], v[194:197], v[62:65]
	v_mfma_f32_16x16x32_bf16 v[46:49], v[66:69], v[202:205], v[46:49]
	v_mfma_f32_16x16x32_bf16 v[38:41], v[146:149], v[202:205], v[38:41]
	v_mfma_f32_16x16x32_bf16 v[30:33], v[66:69], v[212:215], v[30:33]
	v_mfma_f32_16x16x32_bf16 v[22:25], v[146:149], v[212:215], v[22:25]
	v_mfma_f32_16x16x32_bf16 v[14:17], v[66:69], v[220:223], v[14:17]
	v_mfma_f32_16x16x32_bf16 v[6:9], v[146:149], v[220:223], v[6:9]
	v_mfma_f32_16x16x32_bf16 v[58:61], v[178:181], v[190:193], 0
	v_mfma_f32_16x16x32_bf16 v[42:45], v[150:153], v[198:201], 0
	v_mfma_f32_16x16x32_bf16 v[34:37], v[178:181], v[198:201], 0
	v_mfma_f32_16x16x32_bf16 v[26:29], v[150:153], v[208:211], 0
	v_mfma_f32_16x16x32_bf16 v[18:21], v[178:181], v[208:211], 0
	v_mfma_f32_16x16x32_bf16 v[10:13], v[150:153], v[216:219], 0
	v_mfma_f32_16x16x32_bf16 v[2:5], v[178:181], v[216:219], 0
	v_mfma_f32_16x16x32_bf16 v[54:57], v[150:153], v[190:193], 0
	v_mfma_f32_16x16x32_bf16 v[58:61], v[182:185], v[194:197], v[58:61]
	v_mfma_f32_16x16x32_bf16 v[42:45], v[174:177], v[202:205], v[42:45]
	v_mfma_f32_16x16x32_bf16 v[34:37], v[182:185], v[202:205], v[34:37]
	v_mfma_f32_16x16x32_bf16 v[26:29], v[174:177], v[212:215], v[26:29]
	v_mfma_f32_16x16x32_bf16 v[18:21], v[182:185], v[212:215], v[18:21]
	v_mfma_f32_16x16x32_bf16 v[10:13], v[174:177], v[220:223], v[10:13]
	v_mfma_f32_16x16x32_bf16 v[2:5], v[182:185], v[220:223], v[2:5]
	v_mfma_f32_16x16x32_bf16 v[54:57], v[174:177], v[194:197], v[54:57]
	s_setprio 0
	s_barrier
	s_branch .Lpeel_mid_sw
.LBB0_307:
	s_add_u32 s60, s56, 0xfffc0080
	s_addc_u32 s61, s57, -1
	s_and_b64 s[58:59], s[58:59], exec
	s_cselect_b32 s61, s73, s61
	s_cselect_b32 s60, s74, s60
	s_cselect_b32 s59, s75, s13
	s_cselect_b32 s58, s76, s12
	s_add_i32 s80, 0, 0x10000
	s_add_i32 s82, 0, 0x14000
	v_add_u32_e32 v146, s80, v165
	v_add_u32_e32 v182, s82, v165
	ds_read_b128 v[54:57], v146
	ds_read_b128 v[66:69], v146 offset:1024
	ds_read_b128 v[70:73], v146 offset:2048
	ds_read_b128 v[146:149], v146 offset:3072
	ds_read_b128 v[150:153], v182
	ds_read_b128 v[174:177], v182 offset:1024
	ds_read_b128 v[178:181], v182 offset:2048
	ds_read_b128 v[182:185], v182 offset:3072
	v_lshl_add_u64 v[224:225], s[56:57], 0, v[170:171]
	s_add_i32 m0, s64, 0xc000
	ds_read_b128 v[190:193], v188
	ds_read_b128 v[194:197], v188 offset:1024
	ds_read_b128 v[198:201], v188 offset:2048
	ds_read_b128 v[202:205], v188 offset:3072
	ds_read_b128 v[208:211], v188 offset:4096
	ds_read_b128 v[212:215], v188 offset:5120
	ds_read_b128 v[216:219], v188 offset:6144
	ds_read_b128 v[220:223], v188 offset:7168
	global_load_lds_dwordx4 v[224:225], off
	v_lshl_add_u64 v[224:225], s[56:57], 0, v[172:173]
	s_add_i32 m0, s64, 0xe000
	s_nop 0
	global_load_lds_dwordx4 v[224:225], off
	s_waitcnt vmcnt(8)
	s_waitcnt lgkmcnt(0)
	s_barrier
	s_setprio 1
	v_mfma_f32_16x16x32_bf16 v[142:145], v[54:57], v[190:193], v[142:145]
	v_mfma_f32_16x16x32_bf16 v[134:137], v[70:73], v[190:193], v[134:137]
	v_mfma_f32_16x16x32_bf16 v[126:129], v[54:57], v[198:201], v[126:129]
	v_mfma_f32_16x16x32_bf16 v[118:121], v[70:73], v[198:201], v[118:121]
	v_mfma_f32_16x16x32_bf16 v[110:113], v[54:57], v[208:211], v[110:113]
	v_mfma_f32_16x16x32_bf16 v[102:105], v[70:73], v[208:211], v[102:105]
	v_mfma_f32_16x16x32_bf16 v[94:97], v[54:57], v[216:219], v[94:97]
	v_mfma_f32_16x16x32_bf16 v[86:89], v[70:73], v[216:219], v[86:89]
	v_mfma_f32_16x16x32_bf16 v[142:145], v[66:69], v[194:197], v[142:145]
	v_mfma_f32_16x16x32_bf16 v[134:137], v[146:149], v[194:197], v[134:137]
	v_mfma_f32_16x16x32_bf16 v[126:129], v[66:69], v[202:205], v[126:129]
	v_mfma_f32_16x16x32_bf16 v[118:121], v[146:149], v[202:205], v[118:121]
	v_mfma_f32_16x16x32_bf16 v[110:113], v[66:69], v[212:215], v[110:113]
	v_mfma_f32_16x16x32_bf16 v[102:105], v[146:149], v[212:215], v[102:105]
	v_mfma_f32_16x16x32_bf16 v[94:97], v[66:69], v[220:223], v[94:97]
	v_mfma_f32_16x16x32_bf16 v[86:89], v[146:149], v[220:223], v[86:89]
	v_mfma_f32_16x16x32_bf16 v[138:141], v[150:153], v[190:193], v[138:141]
	v_mfma_f32_16x16x32_bf16 v[130:133], v[178:181], v[190:193], v[130:133]
	v_mfma_f32_16x16x32_bf16 v[122:125], v[150:153], v[198:201], v[122:125]
	v_mfma_f32_16x16x32_bf16 v[114:117], v[178:181], v[198:201], v[114:117]
	v_mfma_f32_16x16x32_bf16 v[106:109], v[150:153], v[208:211], v[106:109]
	v_mfma_f32_16x16x32_bf16 v[98:101], v[178:181], v[208:211], v[98:101]
	v_mfma_f32_16x16x32_bf16 v[90:93], v[150:153], v[216:219], v[90:93]
	v_mfma_f32_16x16x32_bf16 v[82:85], v[178:181], v[216:219], v[82:85]
	v_mfma_f32_16x16x32_bf16 v[138:141], v[174:177], v[194:197], v[138:141]
	v_mfma_f32_16x16x32_bf16 v[130:133], v[182:185], v[194:197], v[130:133]
	v_mfma_f32_16x16x32_bf16 v[122:125], v[174:177], v[202:205], v[122:125]
	v_mfma_f32_16x16x32_bf16 v[114:117], v[182:185], v[202:205], v[114:117]
	v_mfma_f32_16x16x32_bf16 v[106:109], v[174:177], v[212:215], v[106:109]
	v_mfma_f32_16x16x32_bf16 v[98:101], v[182:185], v[212:215], v[98:101]
	v_mfma_f32_16x16x32_bf16 v[90:93], v[174:177], v[220:223], v[90:93]
	v_mfma_f32_16x16x32_bf16 v[82:85], v[182:185], v[220:223], v[82:85]
	s_setprio 0
	s_barrier
	s_add_i32 s80, s80, s22
	v_lshl_add_u64 v[224:225], s[58:59], 0, v[158:159]
	s_mov_b32 m0, s80
	ds_read_b128 v[190:193], v188 offset:16384
	ds_read_b128 v[194:197], v188 offset:17408
	ds_read_b128 v[198:201], v188 offset:18432
	ds_read_b128 v[202:205], v188 offset:19456
	ds_read_b128 v[208:211], v188 offset:20480
	ds_read_b128 v[212:215], v188 offset:21504
	ds_read_b128 v[216:219], v188 offset:22528
	ds_read_b128 v[220:223], v188 offset:23552
	global_load_lds_dwordx4 v[224:225], off
	s_add_i32 m0, s80, 0x2000
	s_add_u32 s80, s58, 0x40000
	v_lshl_add_u64 v[226:227], s[58:59], 0, v[154:155]
	s_addc_u32 s81, s59, 0
	s_add_i32 s82, s82, s22
	global_load_lds_dwordx4 v[226:227], off
	v_lshl_add_u64 v[228:229], s[80:81], 0, v[158:159]
	s_mov_b32 m0, s82
	v_lshl_add_u64 v[230:231], s[60:61], 0, v[156:157]
	global_load_lds_dwordx4 v[228:229], off
	v_lshl_add_u64 v[228:229], s[80:81], 0, v[154:155]
	s_add_i32 m0, s82, 0x2000
	s_nop 0
	global_load_lds_dwordx4 v[228:229], off
	v_lshl_add_u64 v[228:229], s[60:61], 0, v[160:161]
	s_mov_b32 m0, s64
	s_nop 0
	global_load_lds_dwordx4 v[228:229], off
	s_mov_b32 m0, s65
	s_nop 0
	global_load_lds_dwordx4 v[230:231], off
	s_waitcnt vmcnt(8)
	s_waitcnt lgkmcnt(0)
	s_barrier
	s_setprio 1
	v_mfma_f32_16x16x32_bf16 v[78:81], v[54:57], v[190:193], v[78:81]
	v_mfma_f32_16x16x32_bf16 v[62:65], v[70:73], v[190:193], v[62:65]
	v_mfma_f32_16x16x32_bf16 v[46:49], v[54:57], v[198:201], v[46:49]
	v_mfma_f32_16x16x32_bf16 v[38:41], v[70:73], v[198:201], v[38:41]
	v_mfma_f32_16x16x32_bf16 v[30:33], v[54:57], v[208:211], v[30:33]
	v_mfma_f32_16x16x32_bf16 v[22:25], v[70:73], v[208:211], v[22:25]
	v_mfma_f32_16x16x32_bf16 v[14:17], v[54:57], v[216:219], v[14:17]
	v_mfma_f32_16x16x32_bf16 v[6:9], v[70:73], v[216:219], v[6:9]
	v_mfma_f32_16x16x32_bf16 v[78:81], v[66:69], v[194:197], v[78:81]
	v_mfma_f32_16x16x32_bf16 v[62:65], v[146:149], v[194:197], v[62:65]
	v_mfma_f32_16x16x32_bf16 v[46:49], v[66:69], v[202:205], v[46:49]
	v_mfma_f32_16x16x32_bf16 v[38:41], v[146:149], v[202:205], v[38:41]
	v_mfma_f32_16x16x32_bf16 v[30:33], v[66:69], v[212:215], v[30:33]
	v_mfma_f32_16x16x32_bf16 v[22:25], v[146:149], v[212:215], v[22:25]
	v_mfma_f32_16x16x32_bf16 v[14:17], v[66:69], v[220:223], v[14:17]
	v_mfma_f32_16x16x32_bf16 v[6:9], v[146:149], v[220:223], v[6:9]
	v_mfma_f32_16x16x32_bf16 v[58:61], v[178:181], v[190:193], v[58:61]
	v_mfma_f32_16x16x32_bf16 v[42:45], v[150:153], v[198:201], v[42:45]
	v_mfma_f32_16x16x32_bf16 v[34:37], v[178:181], v[198:201], v[34:37]
	v_mfma_f32_16x16x32_bf16 v[26:29], v[150:153], v[208:211], v[26:29]
	v_mfma_f32_16x16x32_bf16 v[18:21], v[178:181], v[208:211], v[18:21]
	v_mfma_f32_16x16x32_bf16 v[10:13], v[150:153], v[216:219], v[10:13]
	v_mfma_f32_16x16x32_bf16 v[2:5], v[178:181], v[216:219], v[2:5]
	v_mfma_f32_16x16x32_bf16 v[54:57], v[150:153], v[190:193], v[74:77]
	v_mfma_f32_16x16x32_bf16 v[58:61], v[182:185], v[194:197], v[58:61]
	v_mfma_f32_16x16x32_bf16 v[42:45], v[174:177], v[202:205], v[42:45]
	v_mfma_f32_16x16x32_bf16 v[34:37], v[182:185], v[202:205], v[34:37]
	v_mfma_f32_16x16x32_bf16 v[26:29], v[174:177], v[212:215], v[26:29]
	v_mfma_f32_16x16x32_bf16 v[18:21], v[182:185], v[212:215], v[18:21]
	v_mfma_f32_16x16x32_bf16 v[10:13], v[174:177], v[220:223], v[10:13]
	v_mfma_f32_16x16x32_bf16 v[2:5], v[182:185], v[220:223], v[2:5]
	v_mfma_f32_16x16x32_bf16 v[54:57], v[174:177], v[194:197], v[54:57]
	s_setprio 0
	s_barrier
.Lpeel_mid_sw:
	s_add_i32 s80, 0, 0x18000
	s_add_i32 s81, 0, 0x1c000
	v_add_u32_e32 v146, s80, v165
	v_add_u32_e32 v182, s81, v165
	ds_read_b128 v[66:69], v146
	ds_read_b128 v[70:73], v146 offset:1024
	ds_read_b128 v[74:77], v146 offset:2048
	ds_read_b128 v[146:149], v146 offset:3072
	ds_read_b128 v[150:153], v182
	ds_read_b128 v[174:177], v182 offset:1024
	ds_read_b128 v[178:181], v182 offset:2048
	ds_read_b128 v[182:185], v182 offset:3072
	s_add_u32 s60, s60, 0x40000
	s_addc_u32 s61, s61, 0
	s_mov_b32 m0, s66
	v_lshl_add_u64 v[232:233], s[60:61], 0, v[160:161]
	ds_read_b128 v[190:193], v188 offset:32768
	ds_read_b128 v[194:197], v188 offset:33792
	ds_read_b128 v[198:201], v188 offset:34816
	ds_read_b128 v[202:205], v188 offset:35840
	ds_read_b128 v[208:211], v188 offset:36864
	ds_read_b128 v[212:215], v188 offset:37888
	ds_read_b128 v[216:219], v188 offset:38912
	ds_read_b128 v[220:223], v188 offset:39936
	global_load_lds_dwordx4 v[232:233], off
	v_lshl_add_u64 v[232:233], s[60:61], 0, v[156:157]
	s_mov_b32 m0, s67
	s_nop 0
	global_load_lds_dwordx4 v[232:233], off
	s_waitcnt vmcnt(8)
	s_waitcnt lgkmcnt(0)
	s_barrier
	s_setprio 1
	v_mfma_f32_16x16x32_bf16 v[142:145], v[66:69], v[190:193], v[142:145]
	v_mfma_f32_16x16x32_bf16 v[134:137], v[74:77], v[190:193], v[134:137]
	v_mfma_f32_16x16x32_bf16 v[126:129], v[66:69], v[198:201], v[126:129]
	v_mfma_f32_16x16x32_bf16 v[118:121], v[74:77], v[198:201], v[118:121]
	v_mfma_f32_16x16x32_bf16 v[110:113], v[66:69], v[208:211], v[110:113]
	v_mfma_f32_16x16x32_bf16 v[102:105], v[74:77], v[208:211], v[102:105]
	v_mfma_f32_16x16x32_bf16 v[94:97], v[66:69], v[216:219], v[94:97]
	v_mfma_f32_16x16x32_bf16 v[86:89], v[74:77], v[216:219], v[86:89]
	v_mfma_f32_16x16x32_bf16 v[142:145], v[70:73], v[194:197], v[142:145]
	v_mfma_f32_16x16x32_bf16 v[134:137], v[146:149], v[194:197], v[134:137]
	v_mfma_f32_16x16x32_bf16 v[126:129], v[70:73], v[202:205], v[126:129]
	v_mfma_f32_16x16x32_bf16 v[118:121], v[146:149], v[202:205], v[118:121]
	v_mfma_f32_16x16x32_bf16 v[110:113], v[70:73], v[212:215], v[110:113]
	v_mfma_f32_16x16x32_bf16 v[102:105], v[146:149], v[212:215], v[102:105]
	v_mfma_f32_16x16x32_bf16 v[94:97], v[70:73], v[220:223], v[94:97]
	v_mfma_f32_16x16x32_bf16 v[86:89], v[146:149], v[220:223], v[86:89]
	v_mfma_f32_16x16x32_bf16 v[138:141], v[150:153], v[190:193], v[138:141]
	v_mfma_f32_16x16x32_bf16 v[130:133], v[178:181], v[190:193], v[130:133]
	v_mfma_f32_16x16x32_bf16 v[122:125], v[150:153], v[198:201], v[122:125]
	v_mfma_f32_16x16x32_bf16 v[114:117], v[178:181], v[198:201], v[114:117]
	v_mfma_f32_16x16x32_bf16 v[106:109], v[150:153], v[208:211], v[106:109]
	v_mfma_f32_16x16x32_bf16 v[98:101], v[178:181], v[208:211], v[98:101]
	v_mfma_f32_16x16x32_bf16 v[90:93], v[150:153], v[216:219], v[90:93]
	v_mfma_f32_16x16x32_bf16 v[82:85], v[178:181], v[216:219], v[82:85]
	v_mfma_f32_16x16x32_bf16 v[138:141], v[174:177], v[194:197], v[138:141]
	v_mfma_f32_16x16x32_bf16 v[130:133], v[182:185], v[194:197], v[130:133]
	v_mfma_f32_16x16x32_bf16 v[122:125], v[174:177], v[202:205], v[122:125]
	v_mfma_f32_16x16x32_bf16 v[114:117], v[182:185], v[202:205], v[114:117]
	v_mfma_f32_16x16x32_bf16 v[106:109], v[174:177], v[212:215], v[106:109]
	v_mfma_f32_16x16x32_bf16 v[98:101], v[182:185], v[212:215], v[98:101]
	v_mfma_f32_16x16x32_bf16 v[90:93], v[174:177], v[220:223], v[90:93]
	v_mfma_f32_16x16x32_bf16 v[82:85], v[182:185], v[220:223], v[82:85]
	s_setprio 0
	s_barrier
	s_add_i32 s60, s80, s22
	v_lshl_add_u64 v[224:225], v[224:225], 0, s[0:1]
	s_mov_b32 m0, s60
	ds_read_b128 v[190:193], v188 offset:49152
	ds_read_b128 v[194:197], v188 offset:50176
	ds_read_b128 v[198:201], v188 offset:51200
	ds_read_b128 v[202:205], v188 offset:52224
	ds_read_b128 v[208:211], v188 offset:53248
	ds_read_b128 v[212:215], v188 offset:54272
	ds_read_b128 v[216:219], v188 offset:55296
	ds_read_b128 v[220:223], v188 offset:56320
	global_load_lds_dwordx4 v[224:225], off
	s_add_i32 m0, s60, 0x2000
	s_add_u32 s58, s58, 0x40080
	v_lshl_add_u64 v[224:225], v[226:227], 0, s[0:1]
	s_addc_u32 s59, s59, 0
	s_add_i32 s60, s81, s22
	global_load_lds_dwordx4 v[224:225], off
	v_lshl_add_u64 v[224:225], s[58:59], 0, v[158:159]
	s_mov_b32 m0, s60
	s_nop 0
	global_load_lds_dwordx4 v[224:225], off
	v_lshl_add_u64 v[224:225], s[58:59], 0, v[154:155]
	s_add_i32 m0, s60, 0x2000
	s_nop 0
	global_load_lds_dwordx4 v[224:225], off
	v_lshl_add_u64 v[224:225], v[228:229], 0, s[0:1]
	s_mov_b32 m0, s69
	s_nop 0
	global_load_lds_dwordx4 v[224:225], off
	v_lshl_add_u64 v[224:225], v[230:231], 0, s[0:1]
	s_mov_b32 m0, s70
	s_nop 0
	global_load_lds_dwordx4 v[224:225], off
	s_waitcnt vmcnt(8)
	s_waitcnt lgkmcnt(0)
	s_barrier
	s_setprio 1
	v_mfma_f32_16x16x32_bf16 v[78:81], v[66:69], v[190:193], v[78:81]
	v_mfma_f32_16x16x32_bf16 v[62:65], v[74:77], v[190:193], v[62:65]
	v_mfma_f32_16x16x32_bf16 v[46:49], v[66:69], v[198:201], v[46:49]
	v_mfma_f32_16x16x32_bf16 v[38:41], v[74:77], v[198:201], v[38:41]
	v_mfma_f32_16x16x32_bf16 v[30:33], v[66:69], v[208:211], v[30:33]
	v_mfma_f32_16x16x32_bf16 v[22:25], v[74:77], v[208:211], v[22:25]
	v_mfma_f32_16x16x32_bf16 v[14:17], v[66:69], v[216:219], v[14:17]
	v_mfma_f32_16x16x32_bf16 v[6:9], v[74:77], v[216:219], v[6:9]
	v_mfma_f32_16x16x32_bf16 v[78:81], v[70:73], v[194:197], v[78:81]
	v_mfma_f32_16x16x32_bf16 v[62:65], v[146:149], v[194:197], v[62:65]
	v_mfma_f32_16x16x32_bf16 v[46:49], v[70:73], v[202:205], v[46:49]
	v_mfma_f32_16x16x32_bf16 v[38:41], v[146:149], v[202:205], v[38:41]
	v_mfma_f32_16x16x32_bf16 v[30:33], v[70:73], v[212:215], v[30:33]
	v_mfma_f32_16x16x32_bf16 v[22:25], v[146:149], v[212:215], v[22:25]
	v_mfma_f32_16x16x32_bf16 v[14:17], v[70:73], v[220:223], v[14:17]
	v_mfma_f32_16x16x32_bf16 v[6:9], v[146:149], v[220:223], v[6:9]
	v_mfma_f32_16x16x32_bf16 v[54:57], v[150:153], v[190:193], v[54:57]
	v_mfma_f32_16x16x32_bf16 v[74:77], v[174:177], v[194:197], v[54:57]
	v_mfma_f32_16x16x32_bf16 v[54:57], v[178:181], v[190:193], v[58:61]
	v_mfma_f32_16x16x32_bf16 v[42:45], v[150:153], v[198:201], v[42:45]
	v_mfma_f32_16x16x32_bf16 v[34:37], v[178:181], v[198:201], v[34:37]
	v_mfma_f32_16x16x32_bf16 v[26:29], v[150:153], v[208:211], v[26:29]
	v_mfma_f32_16x16x32_bf16 v[18:21], v[178:181], v[208:211], v[18:21]
	v_mfma_f32_16x16x32_bf16 v[10:13], v[150:153], v[216:219], v[10:13]
	v_mfma_f32_16x16x32_bf16 v[2:5], v[178:181], v[216:219], v[2:5]
	v_mfma_f32_16x16x32_bf16 v[58:61], v[182:185], v[194:197], v[54:57]
	v_mfma_f32_16x16x32_bf16 v[42:45], v[174:177], v[202:205], v[42:45]
	v_mfma_f32_16x16x32_bf16 v[34:37], v[182:185], v[202:205], v[34:37]
	v_mfma_f32_16x16x32_bf16 v[26:29], v[174:177], v[212:215], v[26:29]
	v_mfma_f32_16x16x32_bf16 v[18:21], v[182:185], v[212:215], v[18:21]
	v_mfma_f32_16x16x32_bf16 v[10:13], v[174:177], v[220:223], v[10:13]
	v_mfma_f32_16x16x32_bf16 v[2:5], v[182:185], v[220:223], v[2:5]
	s_setprio 0
	s_barrier
	s_add_i32 s49, s49, 2
	s_add_u32 s56, s56, 0x100
	s_addc_u32 s57, s57, 0
	s_add_u32 s12, s12, 0x100
	s_addc_u32 s13, s13, 0
	s_cmp_gt_u32 s49, 13
	s_cbranch_scc1 .LBB0_310

.LBB0_387:
	s_ashr_i32 s65, s64, 31
	s_lshl_b64 s[12:13], s[64:65], 11
	v_lshl_add_u64 v[130:131], v[174:175], 0, s[12:13]
	s_lshl_b32 s12, s57, 12
	s_add_i32 s69, s90, -2
	s_and_b32 s65, s12, 0x1000
	s_lshl_b64 s[12:13], s[66:67], 10
	s_add_u32 s74, s74, 0x80
	s_addc_u32 s75, s75, 0
	s_add_u32 s67, s76, 0x100
	s_waitcnt lgkmcnt(0)
	v_lshl_add_u64 v[132:133], v[176:177], 0, s[12:13]
	s_addc_u32 s73, s77, 0
	s_mov_b32 s12, 0
	s_mov_b64 s[76:77], 0
	s_add_i32 s12, s12, 2
	s_add_u32 s13, s74, 0x80
	s_addc_u32 vcc_lo, s75, 0
	s_and_b64 s[76:77], s[76:77], exec
	s_cselect_b32 s77, s71, vcc_lo
	s_cselect_b32 s76, s70, s13
	s_cselect_b32 vcc_hi, s45, s73
	s_cselect_b32 vcc_lo, s44, s67
	s_add_i32 s13, 0, 0x10000
	v_add_u32_e32 v1, s13, v208
	s_add_i32 s88, 0, 0x14000
	ds_read_b128 v[134:137], v1
	ds_read_b128 v[138:141], v1 offset:1024
	ds_read_b128 v[142:145], v1 offset:2048
	ds_read_b128 v[146:149], v1 offset:3072
	v_add_u32_e32 v1, s88, v208
	ds_read_b128 v[150:153], v1
	ds_read_b128 v[154:157], v1 offset:1024
	ds_read_b128 v[158:161], v1 offset:2048
	ds_read_b128 v[182:185], v1 offset:3072
	v_lshl_add_u64 v[224:225], s[74:75], 0, v[178:179]
	s_add_i32 m0, s80, 0xc000
	ds_read_b128 v[186:189], v211
	ds_read_b128 v[190:193], v211 offset:1024
	ds_read_b128 v[194:197], v211 offset:2048
	ds_read_b128 v[198:201], v211 offset:3072
	ds_read_b128 v[202:205], v211 offset:4096
	ds_read_b128 v[212:215], v211 offset:5120
	ds_read_b128 v[216:219], v211 offset:6144
	ds_read_b128 v[220:223], v211 offset:7168
	global_load_lds_dwordx4 v[224:225], off
	v_lshl_add_u64 v[224:225], s[74:75], 0, v[180:181]
	s_add_i32 m0, s80, 0xe000
	s_nop 0
	global_load_lds_dwordx4 v[224:225], off
	s_waitcnt vmcnt(8)
	s_waitcnt lgkmcnt(0)
	s_barrier
	s_setprio 1
	v_mfma_f32_16x16x32_bf16 v[126:129], v[134:137], v[186:189], 0
	v_mfma_f32_16x16x32_bf16 v[122:125], v[142:145], v[186:189], 0
	v_mfma_f32_16x16x32_bf16 v[118:121], v[134:137], v[194:197], 0
	v_mfma_f32_16x16x32_bf16 v[114:117], v[142:145], v[194:197], 0
	v_mfma_f32_16x16x32_bf16 v[102:105], v[134:137], v[202:205], 0
	v_mfma_f32_16x16x32_bf16 v[98:101], v[142:145], v[202:205], 0
	v_mfma_f32_16x16x32_bf16 v[86:89], v[134:137], v[216:219], 0
	v_mfma_f32_16x16x32_bf16 v[82:85], v[142:145], v[216:219], 0
	v_mfma_f32_16x16x32_bf16 v[126:129], v[138:141], v[190:193], v[126:129]
	v_mfma_f32_16x16x32_bf16 v[122:125], v[146:149], v[190:193], v[122:125]
	v_mfma_f32_16x16x32_bf16 v[118:121], v[138:141], v[198:201], v[118:121]
	v_mfma_f32_16x16x32_bf16 v[114:117], v[146:149], v[198:201], v[114:117]
	v_mfma_f32_16x16x32_bf16 v[102:105], v[138:141], v[212:215], v[102:105]
	v_mfma_f32_16x16x32_bf16 v[98:101], v[146:149], v[212:215], v[98:101]
	v_mfma_f32_16x16x32_bf16 v[86:89], v[138:141], v[220:223], v[86:89]
	v_mfma_f32_16x16x32_bf16 v[82:85], v[146:149], v[220:223], v[82:85]
	v_mfma_f32_16x16x32_bf16 v[110:113], v[150:153], v[186:189], 0
	v_mfma_f32_16x16x32_bf16 v[106:109], v[158:161], v[186:189], 0
	v_mfma_f32_16x16x32_bf16 v[94:97], v[150:153], v[194:197], 0
	v_mfma_f32_16x16x32_bf16 v[90:93], v[158:161], v[194:197], 0
	v_mfma_f32_16x16x32_bf16 v[78:81], v[150:153], v[202:205], 0
	v_mfma_f32_16x16x32_bf16 v[74:77], v[158:161], v[202:205], 0
	v_mfma_f32_16x16x32_bf16 v[70:73], v[150:153], v[216:219], 0
	v_mfma_f32_16x16x32_bf16 v[66:69], v[158:161], v[216:219], 0
	v_mfma_f32_16x16x32_bf16 v[110:113], v[154:157], v[190:193], v[110:113]
	v_mfma_f32_16x16x32_bf16 v[106:109], v[182:185], v[190:193], v[106:109]
	v_mfma_f32_16x16x32_bf16 v[94:97], v[154:157], v[198:201], v[94:97]
	v_mfma_f32_16x16x32_bf16 v[90:93], v[182:185], v[198:201], v[90:93]
	v_mfma_f32_16x16x32_bf16 v[78:81], v[154:157], v[212:215], v[78:81]
	v_mfma_f32_16x16x32_bf16 v[74:77], v[182:185], v[212:215], v[74:77]
	v_mfma_f32_16x16x32_bf16 v[70:73], v[154:157], v[220:223], v[70:73]
	v_mfma_f32_16x16x32_bf16 v[66:69], v[182:185], v[220:223], v[66:69]
	s_setprio 0
	s_barrier
	s_add_i32 s13, s13, s97
	v_lshl_add_u64 v[224:225], vcc, 0, v[168:169]
	s_mov_b32 m0, s13
	ds_read_b128 v[186:189], v211 offset:16384
	ds_read_b128 v[190:193], v211 offset:17408
	ds_read_b128 v[194:197], v211 offset:18432
	ds_read_b128 v[198:201], v211 offset:19456
	ds_read_b128 v[202:205], v211 offset:20480
	ds_read_b128 v[212:215], v211 offset:21504
	ds_read_b128 v[216:219], v211 offset:22528
	ds_read_b128 v[220:223], v211 offset:23552
	global_load_lds_dwordx4 v[224:225], off
	s_add_i32 m0, s13, 0x2000
	v_lshl_add_u64 v[226:227], vcc, 0, v[172:173]
	s_add_u32 vcc_lo, vcc_lo, s59
	s_addc_u32 vcc_hi, vcc_hi, 0
	s_add_i32 s13, s88, s97
	global_load_lds_dwordx4 v[226:227], off
	v_lshl_add_u64 v[228:229], vcc, 0, v[168:169]
	s_mov_b32 m0, s13
	v_lshl_add_u64 v[230:231], vcc, 0, v[172:173]
	global_load_lds_dwordx4 v[228:229], off
	s_add_i32 m0, s13, 0x2000
	v_lshl_add_u64 v[232:233], s[76:77], 0, v[166:167]
	global_load_lds_dwordx4 v[230:231], off
	s_mov_b32 m0, s80
	v_lshl_add_u64 v[242:243], s[76:77], 0, v[170:171]
	global_load_lds_dwordx4 v[232:233], off
	s_mov_b32 m0, s60
	s_nop 0
	global_load_lds_dwordx4 v[242:243], off
	s_waitcnt vmcnt(8)
	s_waitcnt lgkmcnt(0)
	s_barrier
	s_setprio 1
	v_mfma_f32_16x16x32_bf16 v[62:65], v[134:137], v[186:189], 0
	v_mfma_f32_16x16x32_bf16 v[58:61], v[142:145], v[186:189], 0
	v_mfma_f32_16x16x32_bf16 v[54:57], v[134:137], v[194:197], 0
	v_mfma_f32_16x16x32_bf16 v[50:53], v[142:145], v[194:197], 0
	v_mfma_f32_16x16x32_bf16 v[38:41], v[134:137], v[202:205], 0
	v_mfma_f32_16x16x32_bf16 v[34:37], v[142:145], v[202:205], 0
	v_mfma_f32_16x16x32_bf16 v[22:25], v[134:137], v[216:219], 0
	v_mfma_f32_16x16x32_bf16 v[18:21], v[142:145], v[216:219], 0
	v_mfma_f32_16x16x32_bf16 v[62:65], v[138:141], v[190:193], v[62:65]
	v_mfma_f32_16x16x32_bf16 v[58:61], v[146:149], v[190:193], v[58:61]
	v_mfma_f32_16x16x32_bf16 v[54:57], v[138:141], v[198:201], v[54:57]
	v_mfma_f32_16x16x32_bf16 v[50:53], v[146:149], v[198:201], v[50:53]
	v_mfma_f32_16x16x32_bf16 v[38:41], v[138:141], v[212:215], v[38:41]
	v_mfma_f32_16x16x32_bf16 v[34:37], v[146:149], v[212:215], v[34:37]
	v_mfma_f32_16x16x32_bf16 v[22:25], v[138:141], v[220:223], v[22:25]
	v_mfma_f32_16x16x32_bf16 v[18:21], v[146:149], v[220:223], v[18:21]
	v_mfma_f32_16x16x32_bf16 v[46:49], v[150:153], v[186:189], 0
	v_mfma_f32_16x16x32_bf16 v[42:45], v[158:161], v[186:189], 0
	v_mfma_f32_16x16x32_bf16 v[30:33], v[150:153], v[194:197], 0
	v_mfma_f32_16x16x32_bf16 v[26:29], v[158:161], v[194:197], 0
	v_mfma_f32_16x16x32_bf16 v[14:17], v[150:153], v[202:205], 0
	v_mfma_f32_16x16x32_bf16 v[10:13], v[158:161], v[202:205], 0
	v_mfma_f32_16x16x32_bf16 v[6:9], v[150:153], v[216:219], 0
	v_mfma_f32_16x16x32_bf16 v[2:5], v[158:161], v[216:219], 0
	v_mfma_f32_16x16x32_bf16 v[46:49], v[154:157], v[190:193], v[46:49]
	v_mfma_f32_16x16x32_bf16 v[42:45], v[182:185], v[190:193], v[42:45]
	v_mfma_f32_16x16x32_bf16 v[30:33], v[154:157], v[198:201], v[30:33]
	v_mfma_f32_16x16x32_bf16 v[26:29], v[182:185], v[198:201], v[26:29]
	v_mfma_f32_16x16x32_bf16 v[14:17], v[154:157], v[212:215], v[14:17]
	v_mfma_f32_16x16x32_bf16 v[10:13], v[182:185], v[212:215], v[10:13]
	v_mfma_f32_16x16x32_bf16 v[6:9], v[154:157], v[220:223], v[6:9]
	v_mfma_f32_16x16x32_bf16 v[2:5], v[182:185], v[220:223], v[2:5]
	s_setprio 0
	s_barrier
	s_branch .Lpeel_mid_rs
.LBB0_388:
	s_add_i32 s12, s12, 2
	s_add_u32 s13, s74, 0x80
	s_addc_u32 vcc_lo, s75, 0
	s_and_b64 s[76:77], s[76:77], exec
	s_cselect_b32 s77, s71, vcc_lo
	s_cselect_b32 s76, s70, s13
	s_cselect_b32 vcc_hi, s45, s73
	s_cselect_b32 vcc_lo, s44, s67
	s_add_i32 s13, 0, 0x10000
	v_add_u32_e32 v1, s13, v208
	s_add_i32 s88, 0, 0x14000
	ds_read_b128 v[134:137], v1
	ds_read_b128 v[138:141], v1 offset:1024
	ds_read_b128 v[142:145], v1 offset:2048
	ds_read_b128 v[146:149], v1 offset:3072
	v_add_u32_e32 v1, s88, v208
	ds_read_b128 v[150:153], v1
	ds_read_b128 v[154:157], v1 offset:1024
	ds_read_b128 v[158:161], v1 offset:2048
	ds_read_b128 v[182:185], v1 offset:3072
	v_lshl_add_u64 v[224:225], s[74:75], 0, v[178:179]
	s_add_i32 m0, s80, 0xc000
	ds_read_b128 v[186:189], v211
	ds_read_b128 v[190:193], v211 offset:1024
	ds_read_b128 v[194:197], v211 offset:2048
	ds_read_b128 v[198:201], v211 offset:3072
	ds_read_b128 v[202:205], v211 offset:4096
	ds_read_b128 v[212:215], v211 offset:5120
	ds_read_b128 v[216:219], v211 offset:6144
	ds_read_b128 v[220:223], v211 offset:7168
	global_load_lds_dwordx4 v[224:225], off
	v_lshl_add_u64 v[224:225], s[74:75], 0, v[180:181]
	s_add_i32 m0, s80, 0xe000
	s_nop 0
	global_load_lds_dwordx4 v[224:225], off
	s_waitcnt vmcnt(8)
	s_waitcnt lgkmcnt(0)
	s_barrier
	s_setprio 1
	v_mfma_f32_16x16x32_bf16 v[126:129], v[134:137], v[186:189], v[126:129]
	v_mfma_f32_16x16x32_bf16 v[122:125], v[142:145], v[186:189], v[122:125]
	v_mfma_f32_16x16x32_bf16 v[118:121], v[134:137], v[194:197], v[118:121]
	v_mfma_f32_16x16x32_bf16 v[114:117], v[142:145], v[194:197], v[114:117]
	v_mfma_f32_16x16x32_bf16 v[102:105], v[134:137], v[202:205], v[102:105]
	v_mfma_f32_16x16x32_bf16 v[98:101], v[142:145], v[202:205], v[98:101]
	v_mfma_f32_16x16x32_bf16 v[86:89], v[134:137], v[216:219], v[86:89]
	v_mfma_f32_16x16x32_bf16 v[82:85], v[142:145], v[216:219], v[82:85]
	v_mfma_f32_16x16x32_bf16 v[126:129], v[138:141], v[190:193], v[126:129]
	v_mfma_f32_16x16x32_bf16 v[122:125], v[146:149], v[190:193], v[122:125]
	v_mfma_f32_16x16x32_bf16 v[118:121], v[138:141], v[198:201], v[118:121]
	v_mfma_f32_16x16x32_bf16 v[114:117], v[146:149], v[198:201], v[114:117]
	v_mfma_f32_16x16x32_bf16 v[102:105], v[138:141], v[212:215], v[102:105]
	v_mfma_f32_16x16x32_bf16 v[98:101], v[146:149], v[212:215], v[98:101]
	v_mfma_f32_16x16x32_bf16 v[86:89], v[138:141], v[220:223], v[86:89]
	v_mfma_f32_16x16x32_bf16 v[82:85], v[146:149], v[220:223], v[82:85]
	v_mfma_f32_16x16x32_bf16 v[110:113], v[150:153], v[186:189], v[110:113]
	v_mfma_f32_16x16x32_bf16 v[106:109], v[158:161], v[186:189], v[106:109]
	v_mfma_f32_16x16x32_bf16 v[94:97], v[150:153], v[194:197], v[94:97]
	v_mfma_f32_16x16x32_bf16 v[90:93], v[158:161], v[194:197], v[90:93]
	v_mfma_f32_16x16x32_bf16 v[78:81], v[150:153], v[202:205], v[78:81]
	v_mfma_f32_16x16x32_bf16 v[74:77], v[158:161], v[202:205], v[74:77]
	v_mfma_f32_16x16x32_bf16 v[70:73], v[150:153], v[216:219], v[70:73]
	v_mfma_f32_16x16x32_bf16 v[66:69], v[158:161], v[216:219], v[66:69]
	v_mfma_f32_16x16x32_bf16 v[110:113], v[154:157], v[190:193], v[110:113]
	v_mfma_f32_16x16x32_bf16 v[106:109], v[182:185], v[190:193], v[106:109]
	v_mfma_f32_16x16x32_bf16 v[94:97], v[154:157], v[198:201], v[94:97]
	v_mfma_f32_16x16x32_bf16 v[90:93], v[182:185], v[198:201], v[90:93]
	v_mfma_f32_16x16x32_bf16 v[78:81], v[154:157], v[212:215], v[78:81]
	v_mfma_f32_16x16x32_bf16 v[74:77], v[182:185], v[212:215], v[74:77]
	v_mfma_f32_16x16x32_bf16 v[70:73], v[154:157], v[220:223], v[70:73]
	v_mfma_f32_16x16x32_bf16 v[66:69], v[182:185], v[220:223], v[66:69]
	s_setprio 0
	s_barrier
	s_add_i32 s13, s13, s97
	v_lshl_add_u64 v[224:225], vcc, 0, v[168:169]
	s_mov_b32 m0, s13
	ds_read_b128 v[186:189], v211 offset:16384
	ds_read_b128 v[190:193], v211 offset:17408
	ds_read_b128 v[194:197], v211 offset:18432
	ds_read_b128 v[198:201], v211 offset:19456
	ds_read_b128 v[202:205], v211 offset:20480
	ds_read_b128 v[212:215], v211 offset:21504
	ds_read_b128 v[216:219], v211 offset:22528
	ds_read_b128 v[220:223], v211 offset:23552
	global_load_lds_dwordx4 v[224:225], off
	s_add_i32 m0, s13, 0x2000
	v_lshl_add_u64 v[226:227], vcc, 0, v[172:173]
	s_add_u32 vcc_lo, vcc_lo, s59
	s_addc_u32 vcc_hi, vcc_hi, 0
	s_add_i32 s13, s88, s97
	global_load_lds_dwordx4 v[226:227], off
	v_lshl_add_u64 v[228:229], vcc, 0, v[168:169]
	s_mov_b32 m0, s13
	v_lshl_add_u64 v[230:231], vcc, 0, v[172:173]
	global_load_lds_dwordx4 v[228:229], off
	s_add_i32 m0, s13, 0x2000
	v_lshl_add_u64 v[232:233], s[76:77], 0, v[166:167]
	global_load_lds_dwordx4 v[230:231], off
	s_mov_b32 m0, s80
	v_lshl_add_u64 v[242:243], s[76:77], 0, v[170:171]
	global_load_lds_dwordx4 v[232:233], off
	s_mov_b32 m0, s60
	s_nop 0
	global_load_lds_dwordx4 v[242:243], off
	s_waitcnt vmcnt(8)
	s_waitcnt lgkmcnt(0)
	s_barrier
	s_setprio 1
	v_mfma_f32_16x16x32_bf16 v[62:65], v[134:137], v[186:189], v[62:65]
	v_mfma_f32_16x16x32_bf16 v[58:61], v[142:145], v[186:189], v[58:61]
	v_mfma_f32_16x16x32_bf16 v[54:57], v[134:137], v[194:197], v[54:57]
	v_mfma_f32_16x16x32_bf16 v[50:53], v[142:145], v[194:197], v[50:53]
	v_mfma_f32_16x16x32_bf16 v[38:41], v[134:137], v[202:205], v[38:41]
	v_mfma_f32_16x16x32_bf16 v[34:37], v[142:145], v[202:205], v[34:37]
	v_mfma_f32_16x16x32_bf16 v[22:25], v[134:137], v[216:219], v[22:25]
	v_mfma_f32_16x16x32_bf16 v[18:21], v[142:145], v[216:219], v[18:21]
	v_mfma_f32_16x16x32_bf16 v[62:65], v[138:141], v[190:193], v[62:65]
	v_mfma_f32_16x16x32_bf16 v[58:61], v[146:149], v[190:193], v[58:61]
	v_mfma_f32_16x16x32_bf16 v[54:57], v[138:141], v[198:201], v[54:57]
	v_mfma_f32_16x16x32_bf16 v[50:53], v[146:149], v[198:201], v[50:53]
	v_mfma_f32_16x16x32_bf16 v[38:41], v[138:141], v[212:215], v[38:41]
	v_mfma_f32_16x16x32_bf16 v[34:37], v[146:149], v[212:215], v[34:37]
	v_mfma_f32_16x16x32_bf16 v[22:25], v[138:141], v[220:223], v[22:25]
	v_mfma_f32_16x16x32_bf16 v[18:21], v[146:149], v[220:223], v[18:21]
	v_mfma_f32_16x16x32_bf16 v[46:49], v[150:153], v[186:189], v[46:49]
	v_mfma_f32_16x16x32_bf16 v[42:45], v[158:161], v[186:189], v[42:45]
	v_mfma_f32_16x16x32_bf16 v[30:33], v[150:153], v[194:197], v[30:33]
	v_mfma_f32_16x16x32_bf16 v[26:29], v[158:161], v[194:197], v[26:29]
	v_mfma_f32_16x16x32_bf16 v[14:17], v[150:153], v[202:205], v[14:17]
	v_mfma_f32_16x16x32_bf16 v[10:13], v[158:161], v[202:205], v[10:13]
	v_mfma_f32_16x16x32_bf16 v[6:9], v[150:153], v[216:219], v[6:9]
	v_mfma_f32_16x16x32_bf16 v[2:5], v[158:161], v[216:219], v[2:5]
	v_mfma_f32_16x16x32_bf16 v[46:49], v[154:157], v[190:193], v[46:49]
	v_mfma_f32_16x16x32_bf16 v[42:45], v[182:185], v[190:193], v[42:45]
	v_mfma_f32_16x16x32_bf16 v[30:33], v[154:157], v[198:201], v[30:33]
	v_mfma_f32_16x16x32_bf16 v[26:29], v[182:185], v[198:201], v[26:29]
	v_mfma_f32_16x16x32_bf16 v[14:17], v[154:157], v[212:215], v[14:17]
	v_mfma_f32_16x16x32_bf16 v[10:13], v[182:185], v[212:215], v[10:13]
	v_mfma_f32_16x16x32_bf16 v[6:9], v[154:157], v[220:223], v[6:9]
	v_mfma_f32_16x16x32_bf16 v[2:5], v[182:185], v[220:223], v[2:5]
	s_setprio 0
	s_barrier
.Lpeel_mid_rs:
	s_add_i32 s13, 0, 0x18000
	v_add_u32_e32 v1, s13, v208
	s_add_i32 s88, 0, 0x1c000
	ds_read_b128 v[134:137], v1
	ds_read_b128 v[138:141], v1 offset:1024
	ds_read_b128 v[142:145], v1 offset:2048
	ds_read_b128 v[146:149], v1 offset:3072
	v_add_u32_e32 v1, s88, v208
	ds_read_b128 v[150:153], v1
	ds_read_b128 v[154:157], v1 offset:1024
	ds_read_b128 v[158:161], v1 offset:2048
	ds_read_b128 v[182:185], v1 offset:3072
	s_add_u32 s76, s76, s56
	s_addc_u32 s77, s77, 0
	s_mov_b32 m0, s61
	v_lshl_add_u64 v[244:245], s[76:77], 0, v[166:167]
	ds_read_b128 v[186:189], v211 offset:32768
	ds_read_b128 v[190:193], v211 offset:33792
	ds_read_b128 v[194:197], v211 offset:34816
	ds_read_b128 v[198:201], v211 offset:35840
	ds_read_b128 v[202:205], v211 offset:36864
	ds_read_b128 v[212:215], v211 offset:37888
	ds_read_b128 v[216:219], v211 offset:38912
	ds_read_b128 v[220:223], v211 offset:39936
	global_load_lds_dwordx4 v[244:245], off
	v_lshl_add_u64 v[244:245], s[76:77], 0, v[170:171]
	s_mov_b32 m0, s83
	s_nop 0
	global_load_lds_dwordx4 v[244:245], off
	s_waitcnt vmcnt(8)
	s_waitcnt lgkmcnt(0)
	s_barrier
	s_setprio 1
	v_mfma_f32_16x16x32_bf16 v[126:129], v[134:137], v[186:189], v[126:129]
	v_mfma_f32_16x16x32_bf16 v[122:125], v[142:145], v[186:189], v[122:125]
	v_mfma_f32_16x16x32_bf16 v[118:121], v[134:137], v[194:197], v[118:121]
	v_mfma_f32_16x16x32_bf16 v[114:117], v[142:145], v[194:197], v[114:117]
	v_mfma_f32_16x16x32_bf16 v[102:105], v[134:137], v[202:205], v[102:105]
	v_mfma_f32_16x16x32_bf16 v[98:101], v[142:145], v[202:205], v[98:101]
	v_mfma_f32_16x16x32_bf16 v[86:89], v[134:137], v[216:219], v[86:89]
	v_mfma_f32_16x16x32_bf16 v[82:85], v[142:145], v[216:219], v[82:85]
	v_mfma_f32_16x16x32_bf16 v[126:129], v[138:141], v[190:193], v[126:129]
	v_mfma_f32_16x16x32_bf16 v[122:125], v[146:149], v[190:193], v[122:125]
	v_mfma_f32_16x16x32_bf16 v[118:121], v[138:141], v[198:201], v[118:121]
	v_mfma_f32_16x16x32_bf16 v[114:117], v[146:149], v[198:201], v[114:117]
	v_mfma_f32_16x16x32_bf16 v[102:105], v[138:141], v[212:215], v[102:105]
	v_mfma_f32_16x16x32_bf16 v[98:101], v[146:149], v[212:215], v[98:101]
	v_mfma_f32_16x16x32_bf16 v[86:89], v[138:141], v[220:223], v[86:89]
	v_mfma_f32_16x16x32_bf16 v[82:85], v[146:149], v[220:223], v[82:85]
	v_mfma_f32_16x16x32_bf16 v[110:113], v[150:153], v[186:189], v[110:113]
	v_mfma_f32_16x16x32_bf16 v[106:109], v[158:161], v[186:189], v[106:109]
	v_mfma_f32_16x16x32_bf16 v[94:97], v[150:153], v[194:197], v[94:97]
	v_mfma_f32_16x16x32_bf16 v[90:93], v[158:161], v[194:197], v[90:93]
	v_mfma_f32_16x16x32_bf16 v[78:81], v[150:153], v[202:205], v[78:81]
	v_mfma_f32_16x16x32_bf16 v[74:77], v[158:161], v[202:205], v[74:77]
	v_mfma_f32_16x16x32_bf16 v[70:73], v[150:153], v[216:219], v[70:73]
	v_mfma_f32_16x16x32_bf16 v[66:69], v[158:161], v[216:219], v[66:69]
	v_mfma_f32_16x16x32_bf16 v[110:113], v[154:157], v[190:193], v[110:113]
	v_mfma_f32_16x16x32_bf16 v[106:109], v[182:185], v[190:193], v[106:109]
	v_mfma_f32_16x16x32_bf16 v[94:97], v[154:157], v[198:201], v[94:97]
	v_mfma_f32_16x16x32_bf16 v[90:93], v[182:185], v[198:201], v[90:93]
	v_mfma_f32_16x16x32_bf16 v[78:81], v[154:157], v[212:215], v[78:81]
	v_mfma_f32_16x16x32_bf16 v[74:77], v[182:185], v[212:215], v[74:77]
	v_mfma_f32_16x16x32_bf16 v[70:73], v[154:157], v[220:223], v[70:73]
	v_mfma_f32_16x16x32_bf16 v[66:69], v[182:185], v[220:223], v[66:69]
	s_setprio 0
	s_barrier
	s_add_i32 s13, s13, s97
	v_lshl_add_u64 v[224:225], v[224:225], 0, s[0:1]
	s_mov_b32 m0, s13
	ds_read_b128 v[186:189], v211 offset:49152
	ds_read_b128 v[190:193], v211 offset:50176
	ds_read_b128 v[194:197], v211 offset:51200
	ds_read_b128 v[198:201], v211 offset:52224
	ds_read_b128 v[202:205], v211 offset:53248
	ds_read_b128 v[212:215], v211 offset:54272
	ds_read_b128 v[216:219], v211 offset:55296
	ds_read_b128 v[220:223], v211 offset:56320
	global_load_lds_dwordx4 v[224:225], off
	v_lshl_add_u64 v[224:225], v[226:227], 0, s[0:1]
	s_add_i32 m0, s13, 0x2000
	s_add_i32 s13, s88, s97
	global_load_lds_dwordx4 v[224:225], off
	v_lshl_add_u64 v[224:225], v[228:229], 0, s[0:1]
	s_mov_b32 m0, s13
	s_nop 0
	global_load_lds_dwordx4 v[224:225], off
	v_lshl_add_u64 v[224:225], v[230:231], 0, s[0:1]
	s_add_i32 m0, s13, 0x2000
	s_nop 0
	global_load_lds_dwordx4 v[224:225], off
	v_lshl_add_u64 v[224:225], v[232:233], 0, s[0:1]
	s_mov_b32 m0, s2
	s_nop 0
	global_load_lds_dwordx4 v[224:225], off
	v_lshl_add_u64 v[224:225], v[242:243], 0, s[0:1]
	s_mov_b32 m0, s86
	s_nop 0
	global_load_lds_dwordx4 v[224:225], off
	s_waitcnt vmcnt(8)
	s_waitcnt lgkmcnt(0)
	s_barrier
	s_setprio 1
	v_mfma_f32_16x16x32_bf16 v[62:65], v[134:137], v[186:189], v[62:65]
	v_mfma_f32_16x16x32_bf16 v[58:61], v[142:145], v[186:189], v[58:61]
	v_mfma_f32_16x16x32_bf16 v[54:57], v[134:137], v[194:197], v[54:57]
	v_mfma_f32_16x16x32_bf16 v[50:53], v[142:145], v[194:197], v[50:53]
	v_mfma_f32_16x16x32_bf16 v[38:41], v[134:137], v[202:205], v[38:41]
	v_mfma_f32_16x16x32_bf16 v[34:37], v[142:145], v[202:205], v[34:37]
	v_mfma_f32_16x16x32_bf16 v[22:25], v[134:137], v[216:219], v[22:25]
	v_mfma_f32_16x16x32_bf16 v[18:21], v[142:145], v[216:219], v[18:21]
	v_mfma_f32_16x16x32_bf16 v[62:65], v[138:141], v[190:193], v[62:65]
	v_mfma_f32_16x16x32_bf16 v[58:61], v[146:149], v[190:193], v[58:61]
	v_mfma_f32_16x16x32_bf16 v[54:57], v[138:141], v[198:201], v[54:57]
	v_mfma_f32_16x16x32_bf16 v[50:53], v[146:149], v[198:201], v[50:53]
	v_mfma_f32_16x16x32_bf16 v[38:41], v[138:141], v[212:215], v[38:41]
	v_mfma_f32_16x16x32_bf16 v[34:37], v[146:149], v[212:215], v[34:37]
	v_mfma_f32_16x16x32_bf16 v[22:25], v[138:141], v[220:223], v[22:25]
	v_mfma_f32_16x16x32_bf16 v[18:21], v[146:149], v[220:223], v[18:21]
	v_mfma_f32_16x16x32_bf16 v[46:49], v[150:153], v[186:189], v[46:49]
	v_mfma_f32_16x16x32_bf16 v[42:45], v[158:161], v[186:189], v[42:45]
	v_mfma_f32_16x16x32_bf16 v[30:33], v[150:153], v[194:197], v[30:33]
	v_mfma_f32_16x16x32_bf16 v[26:29], v[158:161], v[194:197], v[26:29]
	v_mfma_f32_16x16x32_bf16 v[14:17], v[150:153], v[202:205], v[14:17]
	v_mfma_f32_16x16x32_bf16 v[10:13], v[158:161], v[202:205], v[10:13]
	v_mfma_f32_16x16x32_bf16 v[6:9], v[150:153], v[216:219], v[6:9]
	v_mfma_f32_16x16x32_bf16 v[2:5], v[158:161], v[216:219], v[2:5]
	v_mfma_f32_16x16x32_bf16 v[46:49], v[154:157], v[190:193], v[46:49]
	v_mfma_f32_16x16x32_bf16 v[42:45], v[182:185], v[190:193], v[42:45]
	v_mfma_f32_16x16x32_bf16 v[30:33], v[154:157], v[198:201], v[30:33]
	v_mfma_f32_16x16x32_bf16 v[26:29], v[182:185], v[198:201], v[26:29]
	v_mfma_f32_16x16x32_bf16 v[14:17], v[154:157], v[212:215], v[14:17]
	v_mfma_f32_16x16x32_bf16 v[10:13], v[182:185], v[212:215], v[10:13]
	v_mfma_f32_16x16x32_bf16 v[6:9], v[154:157], v[220:223], v[6:9]
	v_mfma_f32_16x16x32_bf16 v[2:5], v[182:185], v[220:223], v[2:5]
	s_setprio 0
	s_barrier
	s_add_u32 s74, s74, 0x100
	s_addc_u32 s75, s75, 0
	s_add_u32 s67, s67, 0x100
	s_addc_u32 s73, s73, 0
	s_cmp_ge_i32 s12, s90
	s_cbranch_scc1 .LBB0_396

.LBB0_871:
	s_ashr_i32 s55, s54, 31
	s_lshl_b64 s[12:13], s[54:55], 19
	s_add_u32 s56, s8, s12
	s_addc_u32 s57, s9, s13
	s_and_b64 s[12:13], exec, s[42:43]
	s_cselect_b32 s7, s63, s57
	s_cselect_b32 s45, s62, s56
	s_ashr_i32 s53, s52, 31
	s_lshl_b64 s[12:13], s[52:53], 19
	s_add_u32 s58, s24, s12
	s_addc_u32 s59, s25, s13
	s_and_b64 s[12:13], exec, s[42:43]
	s_cselect_b32 s61, s65, s59
	s_cselect_b32 s75, s64, s58
	s_lshl_b64 s[12:13], s[54:55], 11
	v_lshl_add_u64 v[130:131], v[164:165], 0, s[12:13]
	s_lshl_b32 s12, s74, 12
	s_and_b32 s55, s12, 0x1000
	s_lshl_b64 s[12:13], s[52:53], 10
	v_lshl_add_u64 v[132:133], v[166:167], 0, s[12:13]
	v_readlane_b32 s12, v253, 43
	v_readlane_b32 s13, v253, 44
	s_or_b64 s[42:43], s[42:43], s[12:13]
	s_add_u32 s62, s62, 0x40080
	s_addc_u32 s63, s63, 0
	s_add_u32 s12, s64, 0x100
	s_addc_u32 s13, s65, 0
	s_mov_b32 s53, -2
	s_add_i32 s55, s73, s55
	s_mov_b64 s[64:65], -1
	s_add_u32 s66, s62, 0xfffc0080
	s_addc_u32 s67, s63, -1
	s_and_b64 s[64:65], s[64:65], exec
	s_cselect_b32 s67, s67, s7
	s_cselect_b32 s66, s66, s45
	s_cselect_b32 s65, s13, s61
	s_cselect_b32 s64, s12, s75
	s_add_i32 s76, 0, 0x10000
	s_add_i32 s78, 0, 0x14000
	v_add_u32_e32 v146, s76, v169
	v_add_u32_e32 v190, s78, v169
	ds_read_b128 v[134:137], v146
	ds_read_b128 v[138:141], v146 offset:1024
	ds_read_b128 v[142:145], v146 offset:2048
	ds_read_b128 v[146:149], v146 offset:3072
	ds_read_b128 v[150:153], v190
	ds_read_b128 v[182:185], v190 offset:1024
	ds_read_b128 v[186:189], v190 offset:2048
	ds_read_b128 v[190:193], v190 offset:3072
	v_lshl_add_u64 v[226:227], s[62:63], 0, v[178:179]
	s_add_i32 m0, s22, 0xc000
	ds_read_b128 v[194:197], v250
	ds_read_b128 v[198:201], v250 offset:1024
	ds_read_b128 v[202:205], v250 offset:2048
	ds_read_b128 v[206:209], v250 offset:3072
	ds_read_b128 v[210:213], v250 offset:4096
	ds_read_b128 v[214:217], v250 offset:5120
	ds_read_b128 v[218:221], v250 offset:6144
	ds_read_b128 v[222:225], v250 offset:7168
	global_load_lds_dwordx4 v[226:227], off
	v_lshl_add_u64 v[226:227], s[62:63], 0, v[180:181]
	s_add_i32 m0, s22, 0xe000
	s_nop 0
	global_load_lds_dwordx4 v[226:227], off
	s_waitcnt vmcnt(8)
	s_waitcnt lgkmcnt(0)
	s_barrier
	s_setprio 1
	v_mfma_f32_16x16x32_bf16 v[62:65], v[134:137], v[194:197], 0
	v_mfma_f32_16x16x32_bf16 v[58:61], v[142:145], v[194:197], 0
	v_mfma_f32_16x16x32_bf16 v[54:57], v[134:137], v[202:205], 0
	v_mfma_f32_16x16x32_bf16 v[50:53], v[142:145], v[202:205], 0
	v_mfma_f32_16x16x32_bf16 v[46:49], v[134:137], v[210:213], 0
	v_mfma_f32_16x16x32_bf16 v[42:45], v[142:145], v[210:213], 0
	v_mfma_f32_16x16x32_bf16 v[38:41], v[134:137], v[218:221], 0
	v_mfma_f32_16x16x32_bf16 v[34:37], v[142:145], v[218:221], 0
	v_mfma_f32_16x16x32_bf16 v[62:65], v[138:141], v[198:201], v[62:65]
	v_mfma_f32_16x16x32_bf16 v[58:61], v[146:149], v[198:201], v[58:61]
	v_mfma_f32_16x16x32_bf16 v[54:57], v[138:141], v[206:209], v[54:57]
	v_mfma_f32_16x16x32_bf16 v[50:53], v[146:149], v[206:209], v[50:53]
	v_mfma_f32_16x16x32_bf16 v[46:49], v[138:141], v[214:217], v[46:49]
	v_mfma_f32_16x16x32_bf16 v[42:45], v[146:149], v[214:217], v[42:45]
	v_mfma_f32_16x16x32_bf16 v[38:41], v[138:141], v[222:225], v[38:41]
	v_mfma_f32_16x16x32_bf16 v[34:37], v[146:149], v[222:225], v[34:37]
	v_mfma_f32_16x16x32_bf16 v[126:129], v[150:153], v[194:197], 0
	v_mfma_f32_16x16x32_bf16 v[122:125], v[186:189], v[194:197], 0
	v_mfma_f32_16x16x32_bf16 v[118:121], v[150:153], v[202:205], 0
	v_mfma_f32_16x16x32_bf16 v[114:117], v[186:189], v[202:205], 0
	v_mfma_f32_16x16x32_bf16 v[110:113], v[150:153], v[210:213], 0
	v_mfma_f32_16x16x32_bf16 v[106:109], v[186:189], v[210:213], 0
	v_mfma_f32_16x16x32_bf16 v[102:105], v[150:153], v[218:221], 0
	v_mfma_f32_16x16x32_bf16 v[98:101], v[186:189], v[218:221], 0
	v_mfma_f32_16x16x32_bf16 v[126:129], v[182:185], v[198:201], v[126:129]
	v_mfma_f32_16x16x32_bf16 v[122:125], v[190:193], v[198:201], v[122:125]
	v_mfma_f32_16x16x32_bf16 v[118:121], v[182:185], v[206:209], v[118:121]
	v_mfma_f32_16x16x32_bf16 v[114:117], v[190:193], v[206:209], v[114:117]
	v_mfma_f32_16x16x32_bf16 v[110:113], v[182:185], v[214:217], v[110:113]
	v_mfma_f32_16x16x32_bf16 v[106:109], v[190:193], v[214:217], v[106:109]
	v_mfma_f32_16x16x32_bf16 v[102:105], v[182:185], v[222:225], v[102:105]
	v_mfma_f32_16x16x32_bf16 v[98:101], v[190:193], v[222:225], v[98:101]
	s_setprio 0
	s_barrier
	s_add_i32 s76, s76, s16
	v_lshl_add_u64 v[226:227], s[64:65], 0, v[156:157]
	s_mov_b32 m0, s76
	ds_read_b128 v[194:197], v250 offset:16384
	ds_read_b128 v[198:201], v250 offset:17408
	ds_read_b128 v[202:205], v250 offset:18432
	ds_read_b128 v[206:209], v250 offset:19456
	ds_read_b128 v[210:213], v250 offset:20480
	ds_read_b128 v[214:217], v250 offset:21504
	ds_read_b128 v[218:221], v250 offset:22528
	ds_read_b128 v[222:225], v250 offset:23552
	global_load_lds_dwordx4 v[226:227], off
	s_add_i32 m0, s76, 0x2000
	s_add_u32 s76, s64, 0x40000
	v_lshl_add_u64 v[228:229], s[64:65], 0, v[160:161]
	s_addc_u32 s77, s65, 0
	s_add_i32 s78, s78, s16
	global_load_lds_dwordx4 v[228:229], off
	v_lshl_add_u64 v[230:231], s[76:77], 0, v[156:157]
	s_mov_b32 m0, s78
	v_lshl_add_u64 v[232:233], s[66:67], 0, v[158:159]
	global_load_lds_dwordx4 v[230:231], off
	v_lshl_add_u64 v[230:231], s[76:77], 0, v[160:161]
	s_add_i32 m0, s78, 0x2000
	s_nop 0
	global_load_lds_dwordx4 v[230:231], off
	v_lshl_add_u64 v[230:231], s[66:67], 0, v[154:155]
	s_mov_b32 m0, s22
	s_nop 0
	global_load_lds_dwordx4 v[230:231], off
	s_mov_b32 m0, s23
	s_nop 0
	global_load_lds_dwordx4 v[232:233], off
	s_waitcnt vmcnt(8)
	s_waitcnt lgkmcnt(0)
	s_barrier
	s_setprio 1
	v_mfma_f32_16x16x32_bf16 v[30:33], v[134:137], v[194:197], 0
	v_mfma_f32_16x16x32_bf16 v[26:29], v[142:145], v[194:197], 0
	v_mfma_f32_16x16x32_bf16 v[22:25], v[134:137], v[202:205], 0
	v_mfma_f32_16x16x32_bf16 v[18:21], v[142:145], v[202:205], 0
	v_mfma_f32_16x16x32_bf16 v[14:17], v[134:137], v[210:213], 0
	v_mfma_f32_16x16x32_bf16 v[10:13], v[142:145], v[210:213], 0
	v_mfma_f32_16x16x32_bf16 v[6:9], v[134:137], v[218:221], 0
	v_mfma_f32_16x16x32_bf16 v[2:5], v[142:145], v[218:221], 0
	v_mfma_f32_16x16x32_bf16 v[30:33], v[138:141], v[198:201], v[30:33]
	v_mfma_f32_16x16x32_bf16 v[26:29], v[146:149], v[198:201], v[26:29]
	v_mfma_f32_16x16x32_bf16 v[22:25], v[138:141], v[206:209], v[22:25]
	v_mfma_f32_16x16x32_bf16 v[18:21], v[146:149], v[206:209], v[18:21]
	v_mfma_f32_16x16x32_bf16 v[14:17], v[138:141], v[214:217], v[14:17]
	v_mfma_f32_16x16x32_bf16 v[10:13], v[146:149], v[214:217], v[10:13]
	v_mfma_f32_16x16x32_bf16 v[6:9], v[138:141], v[222:225], v[6:9]
	v_mfma_f32_16x16x32_bf16 v[2:5], v[146:149], v[222:225], v[2:5]
	v_mfma_f32_16x16x32_bf16 v[94:97], v[150:153], v[194:197], 0
	v_mfma_f32_16x16x32_bf16 v[90:93], v[186:189], v[194:197], 0
	v_mfma_f32_16x16x32_bf16 v[86:89], v[150:153], v[202:205], 0
	v_mfma_f32_16x16x32_bf16 v[82:85], v[186:189], v[202:205], 0
	v_mfma_f32_16x16x32_bf16 v[78:81], v[150:153], v[210:213], 0
	v_mfma_f32_16x16x32_bf16 v[74:77], v[186:189], v[210:213], 0
	v_mfma_f32_16x16x32_bf16 v[70:73], v[150:153], v[218:221], 0
	v_mfma_f32_16x16x32_bf16 v[66:69], v[186:189], v[218:221], 0
	v_mfma_f32_16x16x32_bf16 v[94:97], v[182:185], v[198:201], v[94:97]
	v_mfma_f32_16x16x32_bf16 v[90:93], v[190:193], v[198:201], v[90:93]
	v_mfma_f32_16x16x32_bf16 v[86:89], v[182:185], v[206:209], v[86:89]
	v_mfma_f32_16x16x32_bf16 v[82:85], v[190:193], v[206:209], v[82:85]
	v_mfma_f32_16x16x32_bf16 v[78:81], v[182:185], v[214:217], v[78:81]
	v_mfma_f32_16x16x32_bf16 v[74:77], v[190:193], v[214:217], v[74:77]
	v_mfma_f32_16x16x32_bf16 v[70:73], v[182:185], v[222:225], v[70:73]
	v_mfma_f32_16x16x32_bf16 v[66:69], v[190:193], v[222:225], v[66:69]
	s_setprio 0
	s_barrier
	s_branch .Lpeel_mid_st
.LBB0_872:
	s_add_u32 s66, s62, 0xfffc0080
	s_addc_u32 s67, s63, -1
	s_and_b64 s[64:65], s[64:65], exec
	s_cselect_b32 s67, s67, s7
	s_cselect_b32 s66, s66, s45
	s_cselect_b32 s65, s13, s61
	s_cselect_b32 s64, s12, s75
	s_add_i32 s76, 0, 0x10000
	s_add_i32 s78, 0, 0x14000
	v_add_u32_e32 v146, s76, v169
	v_add_u32_e32 v190, s78, v169
	ds_read_b128 v[134:137], v146
	ds_read_b128 v[138:141], v146 offset:1024
	ds_read_b128 v[142:145], v146 offset:2048
	ds_read_b128 v[146:149], v146 offset:3072
	ds_read_b128 v[150:153], v190
	ds_read_b128 v[182:185], v190 offset:1024
	ds_read_b128 v[186:189], v190 offset:2048
	ds_read_b128 v[190:193], v190 offset:3072
	v_lshl_add_u64 v[226:227], s[62:63], 0, v[178:179]
	s_add_i32 m0, s22, 0xc000
	ds_read_b128 v[194:197], v250
	ds_read_b128 v[198:201], v250 offset:1024
	ds_read_b128 v[202:205], v250 offset:2048
	ds_read_b128 v[206:209], v250 offset:3072
	ds_read_b128 v[210:213], v250 offset:4096
	ds_read_b128 v[214:217], v250 offset:5120
	ds_read_b128 v[218:221], v250 offset:6144
	ds_read_b128 v[222:225], v250 offset:7168
	global_load_lds_dwordx4 v[226:227], off
	v_lshl_add_u64 v[226:227], s[62:63], 0, v[180:181]
	s_add_i32 m0, s22, 0xe000
	s_nop 0
	global_load_lds_dwordx4 v[226:227], off
	s_waitcnt vmcnt(8)
	s_waitcnt lgkmcnt(0)
	s_barrier
	s_setprio 1
	v_mfma_f32_16x16x32_bf16 v[62:65], v[134:137], v[194:197], v[62:65]
	v_mfma_f32_16x16x32_bf16 v[58:61], v[142:145], v[194:197], v[58:61]
	v_mfma_f32_16x16x32_bf16 v[54:57], v[134:137], v[202:205], v[54:57]
	v_mfma_f32_16x16x32_bf16 v[50:53], v[142:145], v[202:205], v[50:53]
	v_mfma_f32_16x16x32_bf16 v[46:49], v[134:137], v[210:213], v[46:49]
	v_mfma_f32_16x16x32_bf16 v[42:45], v[142:145], v[210:213], v[42:45]
	v_mfma_f32_16x16x32_bf16 v[38:41], v[134:137], v[218:221], v[38:41]
	v_mfma_f32_16x16x32_bf16 v[34:37], v[142:145], v[218:221], v[34:37]
	v_mfma_f32_16x16x32_bf16 v[62:65], v[138:141], v[198:201], v[62:65]
	v_mfma_f32_16x16x32_bf16 v[58:61], v[146:149], v[198:201], v[58:61]
	v_mfma_f32_16x16x32_bf16 v[54:57], v[138:141], v[206:209], v[54:57]
	v_mfma_f32_16x16x32_bf16 v[50:53], v[146:149], v[206:209], v[50:53]
	v_mfma_f32_16x16x32_bf16 v[46:49], v[138:141], v[214:217], v[46:49]
	v_mfma_f32_16x16x32_bf16 v[42:45], v[146:149], v[214:217], v[42:45]
	v_mfma_f32_16x16x32_bf16 v[38:41], v[138:141], v[222:225], v[38:41]
	v_mfma_f32_16x16x32_bf16 v[34:37], v[146:149], v[222:225], v[34:37]
	v_mfma_f32_16x16x32_bf16 v[126:129], v[150:153], v[194:197], v[126:129]
	v_mfma_f32_16x16x32_bf16 v[122:125], v[186:189], v[194:197], v[122:125]
	v_mfma_f32_16x16x32_bf16 v[118:121], v[150:153], v[202:205], v[118:121]
	v_mfma_f32_16x16x32_bf16 v[114:117], v[186:189], v[202:205], v[114:117]
	v_mfma_f32_16x16x32_bf16 v[110:113], v[150:153], v[210:213], v[110:113]
	v_mfma_f32_16x16x32_bf16 v[106:109], v[186:189], v[210:213], v[106:109]
	v_mfma_f32_16x16x32_bf16 v[102:105], v[150:153], v[218:221], v[102:105]
	v_mfma_f32_16x16x32_bf16 v[98:101], v[186:189], v[218:221], v[98:101]
	v_mfma_f32_16x16x32_bf16 v[126:129], v[182:185], v[198:201], v[126:129]
	v_mfma_f32_16x16x32_bf16 v[122:125], v[190:193], v[198:201], v[122:125]
	v_mfma_f32_16x16x32_bf16 v[118:121], v[182:185], v[206:209], v[118:121]
	v_mfma_f32_16x16x32_bf16 v[114:117], v[190:193], v[206:209], v[114:117]
	v_mfma_f32_16x16x32_bf16 v[110:113], v[182:185], v[214:217], v[110:113]
	v_mfma_f32_16x16x32_bf16 v[106:109], v[190:193], v[214:217], v[106:109]
	v_mfma_f32_16x16x32_bf16 v[102:105], v[182:185], v[222:225], v[102:105]
	v_mfma_f32_16x16x32_bf16 v[98:101], v[190:193], v[222:225], v[98:101]
	s_setprio 0
	s_barrier
	s_add_i32 s76, s76, s16
	v_lshl_add_u64 v[226:227], s[64:65], 0, v[156:157]
	s_mov_b32 m0, s76
	ds_read_b128 v[194:197], v250 offset:16384
	ds_read_b128 v[198:201], v250 offset:17408
	ds_read_b128 v[202:205], v250 offset:18432
	ds_read_b128 v[206:209], v250 offset:19456
	ds_read_b128 v[210:213], v250 offset:20480
	ds_read_b128 v[214:217], v250 offset:21504
	ds_read_b128 v[218:221], v250 offset:22528
	ds_read_b128 v[222:225], v250 offset:23552
	global_load_lds_dwordx4 v[226:227], off
	s_add_i32 m0, s76, 0x2000
	s_add_u32 s76, s64, 0x40000
	v_lshl_add_u64 v[228:229], s[64:65], 0, v[160:161]
	s_addc_u32 s77, s65, 0
	s_add_i32 s78, s78, s16
	global_load_lds_dwordx4 v[228:229], off
	v_lshl_add_u64 v[230:231], s[76:77], 0, v[156:157]
	s_mov_b32 m0, s78
	v_lshl_add_u64 v[232:233], s[66:67], 0, v[158:159]
	global_load_lds_dwordx4 v[230:231], off
	v_lshl_add_u64 v[230:231], s[76:77], 0, v[160:161]
	s_add_i32 m0, s78, 0x2000
	s_nop 0
	global_load_lds_dwordx4 v[230:231], off
	v_lshl_add_u64 v[230:231], s[66:67], 0, v[154:155]
	s_mov_b32 m0, s22
	s_nop 0
	global_load_lds_dwordx4 v[230:231], off
	s_mov_b32 m0, s23
	s_nop 0
	global_load_lds_dwordx4 v[232:233], off
	s_waitcnt vmcnt(8)
	s_waitcnt lgkmcnt(0)
	s_barrier
	s_setprio 1
	v_mfma_f32_16x16x32_bf16 v[30:33], v[134:137], v[194:197], v[30:33]
	v_mfma_f32_16x16x32_bf16 v[26:29], v[142:145], v[194:197], v[26:29]
	v_mfma_f32_16x16x32_bf16 v[22:25], v[134:137], v[202:205], v[22:25]
	v_mfma_f32_16x16x32_bf16 v[18:21], v[142:145], v[202:205], v[18:21]
	v_mfma_f32_16x16x32_bf16 v[14:17], v[134:137], v[210:213], v[14:17]
	v_mfma_f32_16x16x32_bf16 v[10:13], v[142:145], v[210:213], v[10:13]
	v_mfma_f32_16x16x32_bf16 v[6:9], v[134:137], v[218:221], v[6:9]
	v_mfma_f32_16x16x32_bf16 v[2:5], v[142:145], v[218:221], v[2:5]
	v_mfma_f32_16x16x32_bf16 v[30:33], v[138:141], v[198:201], v[30:33]
	v_mfma_f32_16x16x32_bf16 v[26:29], v[146:149], v[198:201], v[26:29]
	v_mfma_f32_16x16x32_bf16 v[22:25], v[138:141], v[206:209], v[22:25]
	v_mfma_f32_16x16x32_bf16 v[18:21], v[146:149], v[206:209], v[18:21]
	v_mfma_f32_16x16x32_bf16 v[14:17], v[138:141], v[214:217], v[14:17]
	v_mfma_f32_16x16x32_bf16 v[10:13], v[146:149], v[214:217], v[10:13]
	v_mfma_f32_16x16x32_bf16 v[6:9], v[138:141], v[222:225], v[6:9]
	v_mfma_f32_16x16x32_bf16 v[2:5], v[146:149], v[222:225], v[2:5]
	v_mfma_f32_16x16x32_bf16 v[94:97], v[150:153], v[194:197], v[94:97]
	v_mfma_f32_16x16x32_bf16 v[90:93], v[186:189], v[194:197], v[90:93]
	v_mfma_f32_16x16x32_bf16 v[86:89], v[150:153], v[202:205], v[86:89]
	v_mfma_f32_16x16x32_bf16 v[82:85], v[186:189], v[202:205], v[82:85]
	v_mfma_f32_16x16x32_bf16 v[78:81], v[150:153], v[210:213], v[78:81]
	v_mfma_f32_16x16x32_bf16 v[74:77], v[186:189], v[210:213], v[74:77]
	v_mfma_f32_16x16x32_bf16 v[70:73], v[150:153], v[218:221], v[70:73]
	v_mfma_f32_16x16x32_bf16 v[66:69], v[186:189], v[218:221], v[66:69]
	v_mfma_f32_16x16x32_bf16 v[94:97], v[182:185], v[198:201], v[94:97]
	v_mfma_f32_16x16x32_bf16 v[90:93], v[190:193], v[198:201], v[90:93]
	v_mfma_f32_16x16x32_bf16 v[86:89], v[182:185], v[206:209], v[86:89]
	v_mfma_f32_16x16x32_bf16 v[82:85], v[190:193], v[206:209], v[82:85]
	v_mfma_f32_16x16x32_bf16 v[78:81], v[182:185], v[214:217], v[78:81]
	v_mfma_f32_16x16x32_bf16 v[74:77], v[190:193], v[214:217], v[74:77]
	v_mfma_f32_16x16x32_bf16 v[70:73], v[182:185], v[222:225], v[70:73]
	v_mfma_f32_16x16x32_bf16 v[66:69], v[190:193], v[222:225], v[66:69]
	s_setprio 0
	s_barrier
.Lpeel_mid_st:
	s_add_i32 s76, 0, 0x18000
	s_add_i32 s77, 0, 0x1c000
	v_add_u32_e32 v146, s76, v169
	v_add_u32_e32 v190, s77, v169
	ds_read_b128 v[134:137], v146
	ds_read_b128 v[138:141], v146 offset:1024
	ds_read_b128 v[142:145], v146 offset:2048
	ds_read_b128 v[146:149], v146 offset:3072
	ds_read_b128 v[150:153], v190
	ds_read_b128 v[182:185], v190 offset:1024
	ds_read_b128 v[186:189], v190 offset:2048
	ds_read_b128 v[190:193], v190 offset:3072
	s_add_u32 s66, s66, 0x40000
	s_addc_u32 s67, s67, 0
	s_mov_b32 m0, s37
	v_lshl_add_u64 v[242:243], s[66:67], 0, v[154:155]
	ds_read_b128 v[194:197], v250 offset:32768
	ds_read_b128 v[198:201], v250 offset:33792
	ds_read_b128 v[202:205], v250 offset:34816
	ds_read_b128 v[206:209], v250 offset:35840
	ds_read_b128 v[210:213], v250 offset:36864
	ds_read_b128 v[214:217], v250 offset:37888
	ds_read_b128 v[218:221], v250 offset:38912
	ds_read_b128 v[222:225], v250 offset:39936
	global_load_lds_dwordx4 v[242:243], off
	v_lshl_add_u64 v[242:243], s[66:67], 0, v[158:159]
	s_mov_b32 m0, s68
	s_nop 0
	global_load_lds_dwordx4 v[242:243], off
	s_waitcnt vmcnt(8)
	s_waitcnt lgkmcnt(0)
	s_barrier
	s_setprio 1
	v_mfma_f32_16x16x32_bf16 v[62:65], v[134:137], v[194:197], v[62:65]
	v_mfma_f32_16x16x32_bf16 v[58:61], v[142:145], v[194:197], v[58:61]
	v_mfma_f32_16x16x32_bf16 v[54:57], v[134:137], v[202:205], v[54:57]
	v_mfma_f32_16x16x32_bf16 v[50:53], v[142:145], v[202:205], v[50:53]
	v_mfma_f32_16x16x32_bf16 v[46:49], v[134:137], v[210:213], v[46:49]
	v_mfma_f32_16x16x32_bf16 v[42:45], v[142:145], v[210:213], v[42:45]
	v_mfma_f32_16x16x32_bf16 v[38:41], v[134:137], v[218:221], v[38:41]
	v_mfma_f32_16x16x32_bf16 v[34:37], v[142:145], v[218:221], v[34:37]
	v_mfma_f32_16x16x32_bf16 v[62:65], v[138:141], v[198:201], v[62:65]
	v_mfma_f32_16x16x32_bf16 v[58:61], v[146:149], v[198:201], v[58:61]
	v_mfma_f32_16x16x32_bf16 v[54:57], v[138:141], v[206:209], v[54:57]
	v_mfma_f32_16x16x32_bf16 v[50:53], v[146:149], v[206:209], v[50:53]
	v_mfma_f32_16x16x32_bf16 v[46:49], v[138:141], v[214:217], v[46:49]
	v_mfma_f32_16x16x32_bf16 v[42:45], v[146:149], v[214:217], v[42:45]
	v_mfma_f32_16x16x32_bf16 v[38:41], v[138:141], v[222:225], v[38:41]
	v_mfma_f32_16x16x32_bf16 v[34:37], v[146:149], v[222:225], v[34:37]
	v_mfma_f32_16x16x32_bf16 v[126:129], v[150:153], v[194:197], v[126:129]
	v_mfma_f32_16x16x32_bf16 v[122:125], v[186:189], v[194:197], v[122:125]
	v_mfma_f32_16x16x32_bf16 v[118:121], v[150:153], v[202:205], v[118:121]
	v_mfma_f32_16x16x32_bf16 v[114:117], v[186:189], v[202:205], v[114:117]
	v_mfma_f32_16x16x32_bf16 v[110:113], v[150:153], v[210:213], v[110:113]
	v_mfma_f32_16x16x32_bf16 v[106:109], v[186:189], v[210:213], v[106:109]
	v_mfma_f32_16x16x32_bf16 v[102:105], v[150:153], v[218:221], v[102:105]
	v_mfma_f32_16x16x32_bf16 v[98:101], v[186:189], v[218:221], v[98:101]
	v_mfma_f32_16x16x32_bf16 v[126:129], v[182:185], v[198:201], v[126:129]
	v_mfma_f32_16x16x32_bf16 v[122:125], v[190:193], v[198:201], v[122:125]
	v_mfma_f32_16x16x32_bf16 v[118:121], v[182:185], v[206:209], v[118:121]
	v_mfma_f32_16x16x32_bf16 v[114:117], v[190:193], v[206:209], v[114:117]
	v_mfma_f32_16x16x32_bf16 v[110:113], v[182:185], v[214:217], v[110:113]
	v_mfma_f32_16x16x32_bf16 v[106:109], v[190:193], v[214:217], v[106:109]
	v_mfma_f32_16x16x32_bf16 v[102:105], v[182:185], v[222:225], v[102:105]
	v_mfma_f32_16x16x32_bf16 v[98:101], v[190:193], v[222:225], v[98:101]
	s_setprio 0
	s_barrier
	s_add_i32 s66, s76, s16
	v_lshl_add_u64 v[226:227], v[226:227], 0, s[0:1]
	s_mov_b32 m0, s66
	ds_read_b128 v[194:197], v250 offset:49152
	ds_read_b128 v[198:201], v250 offset:50176
	ds_read_b128 v[202:205], v250 offset:51200
	ds_read_b128 v[206:209], v250 offset:52224
	ds_read_b128 v[210:213], v250 offset:53248
	ds_read_b128 v[214:217], v250 offset:54272
	ds_read_b128 v[218:221], v250 offset:55296
	ds_read_b128 v[222:225], v250 offset:56320
	global_load_lds_dwordx4 v[226:227], off
	s_add_i32 m0, s66, 0x2000
	s_add_u32 s64, s64, 0x40080
	v_lshl_add_u64 v[226:227], v[228:229], 0, s[0:1]
	s_addc_u32 s65, s65, 0
	s_add_i32 s66, s77, s16
	global_load_lds_dwordx4 v[226:227], off
	v_lshl_add_u64 v[226:227], s[64:65], 0, v[156:157]
	s_mov_b32 m0, s66
	s_nop 0
	global_load_lds_dwordx4 v[226:227], off
	v_lshl_add_u64 v[226:227], s[64:65], 0, v[160:161]
	s_add_i32 m0, s66, 0x2000
	s_nop 0
	global_load_lds_dwordx4 v[226:227], off
	v_lshl_add_u64 v[226:227], v[230:231], 0, s[0:1]
	s_mov_b32 m0, s71
	s_nop 0
	global_load_lds_dwordx4 v[226:227], off
	v_lshl_add_u64 v[226:227], v[232:233], 0, s[0:1]
	s_mov_b32 m0, s72
	s_nop 0
	global_load_lds_dwordx4 v[226:227], off
	s_waitcnt vmcnt(8)
	s_waitcnt lgkmcnt(0)
	s_barrier
	s_setprio 1
	v_mfma_f32_16x16x32_bf16 v[30:33], v[134:137], v[194:197], v[30:33]
	v_mfma_f32_16x16x32_bf16 v[26:29], v[142:145], v[194:197], v[26:29]
	v_mfma_f32_16x16x32_bf16 v[22:25], v[134:137], v[202:205], v[22:25]
	v_mfma_f32_16x16x32_bf16 v[18:21], v[142:145], v[202:205], v[18:21]
	v_mfma_f32_16x16x32_bf16 v[14:17], v[134:137], v[210:213], v[14:17]
	v_mfma_f32_16x16x32_bf16 v[10:13], v[142:145], v[210:213], v[10:13]
	v_mfma_f32_16x16x32_bf16 v[6:9], v[134:137], v[218:221], v[6:9]
	v_mfma_f32_16x16x32_bf16 v[2:5], v[142:145], v[218:221], v[2:5]
	v_mfma_f32_16x16x32_bf16 v[30:33], v[138:141], v[198:201], v[30:33]
	v_mfma_f32_16x16x32_bf16 v[26:29], v[146:149], v[198:201], v[26:29]
	v_mfma_f32_16x16x32_bf16 v[22:25], v[138:141], v[206:209], v[22:25]
	v_mfma_f32_16x16x32_bf16 v[18:21], v[146:149], v[206:209], v[18:21]
	v_mfma_f32_16x16x32_bf16 v[14:17], v[138:141], v[214:217], v[14:17]
	v_mfma_f32_16x16x32_bf16 v[10:13], v[146:149], v[214:217], v[10:13]
	v_mfma_f32_16x16x32_bf16 v[6:9], v[138:141], v[222:225], v[6:9]
	v_mfma_f32_16x16x32_bf16 v[2:5], v[146:149], v[222:225], v[2:5]
	v_mfma_f32_16x16x32_bf16 v[94:97], v[150:153], v[194:197], v[94:97]
	v_mfma_f32_16x16x32_bf16 v[90:93], v[186:189], v[194:197], v[90:93]
	v_mfma_f32_16x16x32_bf16 v[86:89], v[150:153], v[202:205], v[86:89]
	v_mfma_f32_16x16x32_bf16 v[82:85], v[186:189], v[202:205], v[82:85]
	v_mfma_f32_16x16x32_bf16 v[78:81], v[150:153], v[210:213], v[78:81]
	v_mfma_f32_16x16x32_bf16 v[74:77], v[186:189], v[210:213], v[74:77]
	v_mfma_f32_16x16x32_bf16 v[70:73], v[150:153], v[218:221], v[70:73]
	v_mfma_f32_16x16x32_bf16 v[66:69], v[186:189], v[218:221], v[66:69]
	v_mfma_f32_16x16x32_bf16 v[94:97], v[182:185], v[198:201], v[94:97]
	v_mfma_f32_16x16x32_bf16 v[90:93], v[190:193], v[198:201], v[90:93]
	v_mfma_f32_16x16x32_bf16 v[86:89], v[182:185], v[206:209], v[86:89]
	v_mfma_f32_16x16x32_bf16 v[82:85], v[190:193], v[206:209], v[82:85]
	v_mfma_f32_16x16x32_bf16 v[78:81], v[182:185], v[214:217], v[78:81]
	v_mfma_f32_16x16x32_bf16 v[74:77], v[190:193], v[214:217], v[74:77]
	v_mfma_f32_16x16x32_bf16 v[70:73], v[182:185], v[222:225], v[70:73]
	v_mfma_f32_16x16x32_bf16 v[66:69], v[190:193], v[222:225], v[66:69]
	s_setprio 0
	s_barrier
	s_add_i32 s53, s53, 2
	s_add_u32 s62, s62, 0x100
	s_addc_u32 s63, s63, 0
	s_add_u32 s12, s12, 0x100
	s_addc_u32 s13, s13, 0
	s_cmp_gt_u32 s53, 13
	s_cbranch_scc1 .LBB0_875
